# ACT (P7 output / P8 A operand) stored K-blocked: [panel][k-block of 64 cols][row][64] so a P8 K-step reads one contiguous 32 KiB block and a P7 tile writes four contiguous blocks
# speedup vs baseline: 1.0292x; 1.0010x over previous
; __device__ __forceinline__ u32x4 pack8(const f32x4& a, const f32x4& b) { u32x4 w; w.x = cvt_pk_bf16(a[0], a[1]); w.y = cvt_pk_bf16(a[2], a[3]); w.z = cvt_pk_bf16(b[0], b[1]); w.w = cvt_pk_bf16(b[2], b[3]); return w; }
; __device__ __forceinline__ float frsq(float x) { return __builtin_amdgcn_rsqf(x); }
; #define PG8_STAGE(bufoff, gbase, voff) do { _Pragma("unroll") for (int _i = 0; _i < 2; ++_i) \
;         __builtin_amdgcn_global_load_lds((const unsigned*)((const char*)(gbase) + (voff)[_i]), (LAS unsigned*)(lds + (bufoff) + ldsw + _i * 8192), 16, 0, 0); } while (0)
; #define PG8_WAIT_V(n) asm volatile("s_waitcnt vmcnt(" #n ")" ::: "memory")
; #define PG8_BAR __builtin_amdgcn_s_barrier()
; template <class Epi, bool ALIGN_EPI, bool SP2>
; __device__ __forceinline__ void gemm_phase(LAS unsigned char* lds, const int K, const Sched& S, const Epi& E) {
;     ...
;         PG8_STAGE(PG8_SB(0, 0), cB, voffB); PG8_STAGE(PG8_SB(0, 1), cB + hstep, voffB); PG8_STAGE(PG8_SA(0, 0), cA, voffA); PG8_STAGE(PG8_SA(0, 1), cA + hstep, voffA);
;         if (wr == 1) PG8_BAR;
;         PG8_WAIT_V(2); PG8_BAR;
;         PG8_STAGE(PG8_SB(1, 0), cB + kstep, voffB); PG8_STAGE(PG8_SA(1, 0), cA + kstep, voffA); PG8_STAGE(PG8_SB(1, 1), cB + hstep + kstep, voffB);
;         PG8_WAIT_V(6); PG8_BAR;
;     __device__ __forceinline__ void operator()(Acc& acc, const Unit& u, int wr, int wc, int fr, int fq) const {
;     ...
; #pragma unroll
;         for (int ai = 0; ai < 2; ++ai)
; #pragma unroll
;             for (int m = 0; m < 4; ++m) { const int row = row0 + ai * HALF + m * 16; const float rstd = (ACT == 0) ? frsq(ssv[ai][m] * (1.0f / D) + EPS) : 1.0f;
; #pragma unroll
;                 for (int bj = 0; bj < 2; ++bj) { f32x4 a = acc[ai][bj][m][0] * rstd, b = acc[ai][bj][m][1] * rstd;
;                     if (ACT == 1) {
; #pragma unroll
;                         for (int i = 0; i < 4; ++i) { const float x = fmaxf(a[i], 0.f), y = fmaxf(b[i], 0.f); a[i] = x * x; b[i] = y * y; } }
;                     *(u32x4*)(O + (size_t)row * ldc + col0 + bj * HALF) = pack8(a, b); }
.LBB0_1082:
	s_add_u32 s12, s92, 0xf000000
	s_addc_u32 s13, s93, 0
	s_lshl_b32 s14, s14, 5
	s_lshl_b32 s58, s15, 6
	s_lshl_b32 s17, s15, 13
	s_and_b32 s59, s14, 0x60
	s_mov_b64 s[14:15], 0x80
	s_add_i32 m0, s54, 0x18000
	v_lshl_add_u64 v[6:7], v[6:7], 0, s[14:15]
	s_lshl_b32 s20, s59, 7
	s_waitcnt vmcnt(2)
	s_barrier
	global_load_lds_dwordx4 v[6:7], off
	v_lshl_add_u64 v[2:3], v[2:3], 0, s[14:15]
	s_add_i32 m0, s54, 0x1a000
	s_add_i32 s60, s54, 0x8000
	s_add_i32 s61, s54, 0xa000
	global_load_lds_dwordx4 v[2:3], off
	v_lshl_add_u64 v[0:1], v[0:1], 0, s[14:15]
	s_mov_b32 m0, s60
	s_add_u32 s18, s44, 0x40080
	global_load_lds_dwordx4 v[0:1], off
	v_lshl_add_u64 v[0:1], v[4:5], 0, s[14:15]
	s_mov_b32 m0, s61
	s_addc_u32 s19, s45, 0
	global_load_lds_dwordx4 v[0:1], off
	s_add_i32 m0, s54, 0x1c000
	v_lshl_add_u64 v[0:1], s[18:19], 0, v[132:133]
	global_load_lds_dwordx4 v[0:1], off
	v_lshl_add_u64 v[0:1], s[18:19], 0, v[128:129]
	s_add_i32 m0, s54, 0x1e000
	v_bfe_u32 v141, v228, 4, 2
	global_load_lds_dwordx4 v[0:1], off
	v_and_b32_e32 v140, 15, v228
	v_lshlrev_b32_e32 v0, 4, v141
	v_lshlrev_b32_e32 v2, 2, v228
	v_lshl_or_b32 v1, v140, 6, v0
	v_and_b32_e32 v2, 32, v2
	v_bitop3_b32 v1, v1, s17, v2 bitop3:0xde
	v_lshlrev_b32_e32 v3, 6, v228
	s_movk_i32 s17, 0x3c0
	v_and_or_b32 v0, v3, s17, v0
	v_bitop3_b32 v142, s20, v0, v2 bitop3:0xf6
	v_lshlrev_b32_e32 v0, 8, v228
	v_and_b32_e32 v0, 0x38000, v0
	v_lshlrev_b32_e32 v2, 11, v11
	v_or3_b32 v0, v9, v0, v2
	v_add_u32_e32 v136, v0, v10
	v_lshlrev_b32_e32 v0, 4, v8
	s_waitcnt vmcnt(6)
	s_cmpk_lt_u32 s16, 0x100
	v_and_b32_e32 v0, 0x78000, v0
	s_cselect_b64 s[16:17], -1, 0
	v_or3_b32 v0, v9, v0, v2
	s_add_i32 s62, 0, 0x10000
	s_add_i32 s63, 0, 0x14000
	v_mov_b32_e32 v137, v133
	v_add_u32_e32 v138, v0, v10
	v_mov_b32_e32 v139, v133
	v_add_u32_e32 v143, s62, v142
	v_add_u32_e32 v144, s63, v142
	v_add_u32_e32 v145, 0, v1
	s_mov_b64 s[18:19], 0x800
	s_mov_b32 s64, 0x800
	s_mov_b32 s65, 0x1000
	s_mov_b64 s[20:21], 0x1800
	s_mov_b32 s66, 0x1800
	s_mov_b64 s[22:23], 0x4000
	s_mov_b32 s67, 0x4000
	s_mov_b64 s[24:25], 0x4800
	s_mov_b32 s68, 0x4800
	s_mov_b64 s[26:27], 0x5000
	s_mov_b32 s69, 0x5000
	s_mov_b64 s[28:29], 0x5800
	s_mov_b32 s70, 0x5800
	s_barrier
	s_branch .LBB0_1085

; __device__ __forceinline__ u32x4 pack8(const f32x4& a, const f32x4& b) { u32x4 w; w.x = cvt_pk_bf16(a[0], a[1]); w.y = cvt_pk_bf16(a[2], a[3]); w.z = cvt_pk_bf16(b[0], b[1]); w.w = cvt_pk_bf16(b[2], b[3]); return w; }
; __device__ __forceinline__ float frsq(float x) { return __builtin_amdgcn_rsqf(x); }
;     __device__ __forceinline__ void operator()(Acc& acc, const Unit& u, int wr, int wc, int fr, int fq) const {
;     ...
;             for (int m = 0; m < 4; ++m) { const int row = row0 + ai * HALF + m * 16; const float rstd = (ACT == 0) ? frsq(ssv[ai][m] * (1.0f / D) + EPS) : 1.0f;
; #pragma unroll
;                 for (int bj = 0; bj < 2; ++bj) { f32x4 a = acc[ai][bj][m][0] * rstd, b = acc[ai][bj][m][1] * rstd;
;                     if (ACT == 1) {
; #pragma unroll
;                         for (int i = 0; i < 4; ++i) { const float x = fmaxf(a[i], 0.f), y = fmaxf(b[i], 0.f); a[i] = x * x; b[i] = y * y; } }
;                     *(u32x4*)(O + (size_t)row * ldc + col0 + bj * HALF) = pack8(a, b); }
.LBB0_1091:
	s_mov_b64 s[98:99], 0x10000
	s_mov_b64 s[100:101], 0x1000
	v_lshrrev_b32_e32 v222, 6, v228
	v_mul_u32_u24_e32 v222, 0x500, v222
	v_add_u32_e32 v222, 0x20000, v222
	v_mul_u32_u24_e32 v223, 0x50, v140
	v_lshl_add_u32 v223, v141, 4, v223
	v_add_u32_e32 v220, v222, v223
	v_bfe_u32 v223, v228, 2, 4
	v_mul_u32_u24_e32 v223, 0x50, v223
	v_and_b32_e32 v221, 3, v228
	v_lshl_add_u32 v223, v221, 4, v223
	v_add_u32_e32 v221, v222, v223
	v_bfe_u32 v146, v228, 2, 4
	v_and_b32_e32 v147, 3, v228
	s_lshl_b32 s6, s6, 8
	s_add_i32 s6, s6, s58
	v_add_u32_e32 v146, s6, v146
	s_lshl_b32 s6, s71, 8
	v_max_f32_e32 v122, 0, v122
	s_or_b32 s6, s6, s59
	v_max_f32_e32 v124, 0, v124
	v_max_f32_e32 v120, 0, v120
	v_max_f32_e32 v121, 0, v121
	v_mul_f32_e32 v150, v122, v122
	v_max_f32_e32 v122, v127, v127
	v_lshl_add_u32 v148, v147, 3, s6
	v_ashrrev_i32_e32 v147, 31, v146
	v_mul_f32_e32 v124, v124, v124
	v_mul_f32_e32 v120, v120, v120
	v_max_f32_e32 v125, 0, v125
	v_mul_f32_e32 v121, v121, v121
	v_max_f32_e32 v126, 0, v126
	v_max_f32_e32 v122, 0, v122
	v_max_f32_e32 v123, 0, v123
	v_mul_f32_e32 v125, v125, v125
	v_mul_f32_e32 v126, v126, v126
	v_mul_f32_e32 v127, v122, v122
	v_mul_f32_e32 v151, v123, v123
	v_cvt_pk_bf16_f32 v122, v124, v125
	v_cvt_pk_bf16_f32 v123, v126, v127
	v_cvt_pk_bf16_f32 v124, v120, v121
	v_and_b32_e32 v120, 0xff, v146
	v_lshlrev_b32_e32 v120, 7, v120
	v_and_b32_e32 v121, 63, v148
	v_lshl_add_u32 v120, v121, 1, v120
	v_lshrrev_b32_e32 v121, 6, v148
	v_lshl_add_u32 v120, v121, 15, v120
	v_lshrrev_b32_e32 v121, 8, v146
	v_lshl_add_u32 v120, v121, 21, v120
	v_mov_b32_e32 v121, 0
	v_lshl_add_u64 v[120:121], s[12:13], 0, v[120:121]
	v_ashrrev_i32_e32 v149, 31, v148
	v_max_f32_e32 v112, 0, v112
	v_cvt_pk_bf16_f32 v125, v150, v151
	ds_write_b128 v220, v[122:125]
	ds_read_b128 v[232:235], v221
	v_mov_b64_e32 v[240:241], v[120:121]
	v_max_f32_e32 v113, 0, v113
	v_max_f32_e32 v114, 0, v114
	v_mul_f32_e32 v122, v112, v112
	v_max_f32_e32 v112, v117, v117
	v_max_f32_e32 v112, 0, v112
	v_mul_f32_e32 v117, v113, v113
	v_max_f32_e32 v113, v118, v118
	v_mul_f32_e32 v118, v114, v114
	v_max_f32_e32 v114, v119, v119
	v_max_f32_e32 v116, 0, v116
	v_mul_f32_e32 v112, v112, v112
	v_max_f32_e32 v113, 0, v113
	v_max_f32_e32 v114, 0, v114
	v_max_f32_e32 v115, 0, v115
	v_mul_f32_e32 v116, v116, v116
	v_mul_f32_e32 v113, v113, v113
	v_mul_f32_e32 v114, v114, v114
	v_mul_f32_e32 v115, v115, v115
	v_cvt_pk_bf16_f32 v112, v116, v112
	v_max_f32_e32 v104, 0, v104
	v_max_f32_e32 v105, 0, v105
	v_max_f32_e32 v106, 0, v106
	v_cvt_pk_bf16_f32 v113, v113, v114
	v_cvt_pk_bf16_f32 v114, v122, v117
	v_cvt_pk_bf16_f32 v115, v118, v115
	ds_write_b128 v220, v[112:115]
	ds_read_b128 v[236:239], v221
	v_mov_b64_e32 v[242:243], v[120:121]
	v_lshl_add_u64 v[242:243], v[242:243], 0, s[98:99]
	s_waitcnt lgkmcnt(2)
	global_store_dwordx4 v[240:241], v[232:235], off
	s_nop 1
	v_mul_f32_e32 v112, v104, v104
	v_max_f32_e32 v104, v109, v109
	v_mul_f32_e32 v109, v105, v105
	v_max_f32_e32 v105, v110, v110
	v_mul_f32_e32 v110, v106, v106
	v_max_f32_e32 v106, v111, v111
	v_max_f32_e32 v104, 0, v104
	v_max_f32_e32 v105, 0, v105
	v_max_f32_e32 v106, 0, v106
	v_max_f32_e32 v107, 0, v107
	v_max_f32_e32 v108, 0, v108
	v_mul_f32_e32 v104, v104, v104
	v_mul_f32_e32 v105, v105, v105
	v_mul_f32_e32 v106, v106, v106
	v_mul_f32_e32 v107, v107, v107
	v_mul_f32_e32 v108, v108, v108
	v_cvt_pk_bf16_f32 v104, v108, v104
	v_cvt_pk_bf16_f32 v105, v105, v106
	v_cvt_pk_bf16_f32 v106, v112, v109
	v_cvt_pk_bf16_f32 v107, v110, v107
	v_add_co_u32_e32 v110, vcc, s64, v120
	s_nop 0
	v_addc_co_u32_e32 v111, vcc, 0, v121, vcc
	v_max_f32_e32 v96, 0, v96
	ds_write_b128 v220, v[104:107]
	ds_read_b128 v[232:235], v221
	v_mov_b64_e32 v[240:241], v[110:111]
	s_waitcnt lgkmcnt(2)
	global_store_dwordx4 v[242:243], v[236:239], off
	v_max_f32_e32 v97, 0, v97
	v_max_f32_e32 v98, 0, v98
	v_mul_f32_e32 v104, v96, v96
	v_max_f32_e32 v96, v101, v101
	v_max_f32_e32 v96, 0, v96
	v_mul_f32_e32 v101, v97, v97
	v_max_f32_e32 v97, v102, v102
	v_mul_f32_e32 v102, v98, v98
	v_max_f32_e32 v98, v103, v103
	v_max_f32_e32 v100, 0, v100
	v_mul_f32_e32 v96, v96, v96
	v_max_f32_e32 v97, 0, v97
	v_max_f32_e32 v98, 0, v98
	v_max_f32_e32 v99, 0, v99
	v_lshl_add_u64 v[108:109], v[120:121], 0, s[18:19]
	v_mul_f32_e32 v100, v100, v100
	v_mul_f32_e32 v97, v97, v97
	v_mul_f32_e32 v98, v98, v98
	v_mul_f32_e32 v99, v99, v99
	v_cvt_pk_bf16_f32 v96, v100, v96
	v_max_f32_e32 v88, 0, v88
	v_max_f32_e32 v89, 0, v89
	v_max_f32_e32 v90, 0, v90
	v_cvt_pk_bf16_f32 v97, v97, v98
	v_cvt_pk_bf16_f32 v98, v104, v101
	v_cvt_pk_bf16_f32 v99, v102, v99
	ds_write_b128 v220, v[96:99]
	ds_read_b128 v[236:239], v221
	v_mov_b64_e32 v[242:243], v[108:109]
	v_lshl_add_u64 v[242:243], v[242:243], 0, s[98:99]
	s_waitcnt lgkmcnt(2)
	global_store_dwordx4 v[240:241], v[232:235], off
	s_nop 1
	v_mul_f32_e32 v96, v88, v88
	v_max_f32_e32 v88, v93, v93
	v_mul_f32_e32 v93, v89, v89
	v_max_f32_e32 v89, v94, v94
	v_mul_f32_e32 v94, v90, v90
	v_max_f32_e32 v90, v95, v95
	v_max_f32_e32 v88, 0, v88
	v_max_f32_e32 v89, 0, v89
	v_max_f32_e32 v90, 0, v90
	v_max_f32_e32 v91, 0, v91
	v_max_f32_e32 v92, 0, v92
	v_mul_f32_e32 v88, v88, v88
	v_mul_f32_e32 v89, v89, v89
	v_mul_f32_e32 v90, v90, v90
	v_mul_f32_e32 v91, v91, v91
	v_mul_f32_e32 v92, v92, v92
	v_cvt_pk_bf16_f32 v88, v92, v88
	v_cvt_pk_bf16_f32 v89, v89, v90
	v_cvt_pk_bf16_f32 v90, v96, v93
	v_cvt_pk_bf16_f32 v91, v94, v91
	v_add_co_u32_e32 v94, vcc, s65, v120
	s_nop 0
	v_addc_co_u32_e32 v95, vcc, 0, v121, vcc
	v_max_f32_e32 v80, 0, v80
	ds_write_b128 v220, v[88:91]
	ds_read_b128 v[232:235], v221
	v_mov_b64_e32 v[240:241], v[94:95]
	s_waitcnt lgkmcnt(2)
; __device__ __forceinline__ u32x4 pack8(const f32x4& a, const f32x4& b) { u32x4 w; w.x = cvt_pk_bf16(a[0], a[1]); w.y = cvt_pk_bf16(a[2], a[3]); w.z = cvt_pk_bf16(b[0], b[1]); w.w = cvt_pk_bf16(b[2], b[3]); return w; }
; __device__ __forceinline__ float frsq(float x) { return __builtin_amdgcn_rsqf(x); }
;     __device__ __forceinline__ void operator()(Acc& acc, const Unit& u, int wr, int wc, int fr, int fq) const {
;     ...
;             for (int m = 0; m < 4; ++m) { const int row = row0 + ai * HALF + m * 16; const float rstd = (ACT == 0) ? frsq(ssv[ai][m] * (1.0f / D) + EPS) : 1.0f;
; #pragma unroll
;                 for (int bj = 0; bj < 2; ++bj) { f32x4 a = acc[ai][bj][m][0] * rstd, b = acc[ai][bj][m][1] * rstd;
;                     if (ACT == 1) {
; #pragma unroll
;                         for (int i = 0; i < 4; ++i) { const float x = fmaxf(a[i], 0.f), y = fmaxf(b[i], 0.f); a[i] = x * x; b[i] = y * y; } }
;                     *(u32x4*)(O + (size_t)row * ldc + col0 + bj * HALF) = pack8(a, b); }
	global_store_dwordx4 v[242:243], v[236:239], off
	v_max_f32_e32 v81, 0, v81
	v_max_f32_e32 v82, 0, v82
	v_mul_f32_e32 v88, v80, v80
	v_max_f32_e32 v80, v85, v85
	v_max_f32_e32 v80, 0, v80
	v_mul_f32_e32 v85, v81, v81
	v_max_f32_e32 v81, v86, v86
	v_mul_f32_e32 v86, v82, v82
	v_max_f32_e32 v82, v87, v87
	v_max_f32_e32 v84, 0, v84
	v_mul_f32_e32 v80, v80, v80
	v_max_f32_e32 v81, 0, v81
	v_max_f32_e32 v82, 0, v82
	v_max_f32_e32 v83, 0, v83
	v_lshl_add_u64 v[92:93], v[120:121], 0, s[100:101]
	v_mul_f32_e32 v84, v84, v84
	v_mul_f32_e32 v81, v81, v81
	v_mul_f32_e32 v82, v82, v82
	v_mul_f32_e32 v83, v83, v83
	v_cvt_pk_bf16_f32 v80, v84, v80
	v_max_f32_e32 v72, 0, v72
	v_max_f32_e32 v73, 0, v73
	v_max_f32_e32 v74, 0, v74
	v_cvt_pk_bf16_f32 v81, v81, v82
	v_cvt_pk_bf16_f32 v82, v88, v85
	v_cvt_pk_bf16_f32 v83, v86, v83
	ds_write_b128 v220, v[80:83]
	ds_read_b128 v[236:239], v221
	v_mov_b64_e32 v[242:243], v[92:93]
	v_lshl_add_u64 v[242:243], v[242:243], 0, s[98:99]
	s_waitcnt lgkmcnt(2)
	global_store_dwordx4 v[240:241], v[232:235], off
	s_nop 1
	v_mul_f32_e32 v80, v72, v72
	v_max_f32_e32 v72, v77, v77
	v_mul_f32_e32 v77, v73, v73
	v_max_f32_e32 v73, v78, v78
	v_mul_f32_e32 v78, v74, v74
	v_max_f32_e32 v74, v79, v79
	v_max_f32_e32 v72, 0, v72
	v_max_f32_e32 v73, 0, v73
	v_max_f32_e32 v74, 0, v74
	v_max_f32_e32 v75, 0, v75
	v_max_f32_e32 v76, 0, v76
	v_mul_f32_e32 v72, v72, v72
	v_mul_f32_e32 v73, v73, v73
	v_mul_f32_e32 v74, v74, v74
	v_mul_f32_e32 v75, v75, v75
	v_mul_f32_e32 v76, v76, v76
	v_cvt_pk_bf16_f32 v72, v76, v72
	v_cvt_pk_bf16_f32 v73, v73, v74
	v_cvt_pk_bf16_f32 v74, v80, v77
	v_cvt_pk_bf16_f32 v75, v78, v75
	v_add_co_u32_e32 v78, vcc, s66, v120
	s_nop 0
	v_addc_co_u32_e32 v79, vcc, 0, v121, vcc
	v_max_f32_e32 v64, 0, v64
	ds_write_b128 v220, v[72:75]
	ds_read_b128 v[232:235], v221
	v_mov_b64_e32 v[240:241], v[78:79]
	s_waitcnt lgkmcnt(2)
	global_store_dwordx4 v[242:243], v[236:239], off
	v_max_f32_e32 v65, 0, v65
	v_max_f32_e32 v66, 0, v66
	v_mul_f32_e32 v72, v64, v64
	v_max_f32_e32 v64, v69, v69
	v_max_f32_e32 v64, 0, v64
	v_mul_f32_e32 v69, v65, v65
	v_max_f32_e32 v65, v70, v70
	v_mul_f32_e32 v70, v66, v66
	v_max_f32_e32 v66, v71, v71
	v_max_f32_e32 v68, 0, v68
	v_mul_f32_e32 v64, v64, v64
	v_max_f32_e32 v65, 0, v65
	v_max_f32_e32 v66, 0, v66
	v_max_f32_e32 v67, 0, v67
	v_lshl_add_u64 v[76:77], v[120:121], 0, s[20:21]
	v_mul_f32_e32 v68, v68, v68
	v_mul_f32_e32 v65, v65, v65
	v_mul_f32_e32 v66, v66, v66
	v_mul_f32_e32 v67, v67, v67
	v_cvt_pk_bf16_f32 v64, v68, v64
	v_max_f32_e32 v56, 0, v56
	v_max_f32_e32 v57, 0, v57
	v_max_f32_e32 v58, 0, v58
	v_cvt_pk_bf16_f32 v65, v65, v66
	v_cvt_pk_bf16_f32 v66, v72, v69
	v_cvt_pk_bf16_f32 v67, v70, v67
	ds_write_b128 v220, v[64:67]
	ds_read_b128 v[236:239], v221
	v_mov_b64_e32 v[242:243], v[76:77]
	v_lshl_add_u64 v[242:243], v[242:243], 0, s[98:99]
	s_waitcnt lgkmcnt(2)
	global_store_dwordx4 v[240:241], v[232:235], off
	s_nop 1
	v_mul_f32_e32 v64, v56, v56
	v_max_f32_e32 v56, v61, v61
	v_mul_f32_e32 v61, v57, v57
	v_max_f32_e32 v57, v62, v62
	v_mul_f32_e32 v62, v58, v58
	v_max_f32_e32 v58, v63, v63
	v_max_f32_e32 v56, 0, v56
	v_max_f32_e32 v57, 0, v57
	v_max_f32_e32 v58, 0, v58
	v_max_f32_e32 v59, 0, v59
	v_max_f32_e32 v60, 0, v60
	v_mul_f32_e32 v56, v56, v56
	v_mul_f32_e32 v57, v57, v57
	v_mul_f32_e32 v58, v58, v58
	v_mul_f32_e32 v59, v59, v59
	v_mul_f32_e32 v60, v60, v60
	v_cvt_pk_bf16_f32 v56, v60, v56
	v_cvt_pk_bf16_f32 v57, v57, v58
	v_cvt_pk_bf16_f32 v58, v64, v61
	v_cvt_pk_bf16_f32 v59, v62, v59
	v_add_co_u32_e32 v62, vcc, s67, v120
	s_nop 0
	v_addc_co_u32_e32 v63, vcc, 0, v121, vcc
	v_max_f32_e32 v48, 0, v48
	ds_write_b128 v220, v[56:59]
	ds_read_b128 v[232:235], v221
	v_mov_b64_e32 v[240:241], v[62:63]
	s_waitcnt lgkmcnt(2)
	global_store_dwordx4 v[242:243], v[236:239], off
	v_max_f32_e32 v49, 0, v49
	v_max_f32_e32 v50, 0, v50
	v_mul_f32_e32 v56, v48, v48
	v_max_f32_e32 v48, v53, v53
	v_max_f32_e32 v48, 0, v48
	v_mul_f32_e32 v53, v49, v49
	v_max_f32_e32 v49, v54, v54
	v_mul_f32_e32 v54, v50, v50
	v_max_f32_e32 v50, v55, v55
	v_max_f32_e32 v52, 0, v52
	v_mul_f32_e32 v48, v48, v48
	v_max_f32_e32 v49, 0, v49
	v_max_f32_e32 v50, 0, v50
	v_max_f32_e32 v51, 0, v51
	v_lshl_add_u64 v[60:61], v[120:121], 0, s[22:23]
	v_mul_f32_e32 v52, v52, v52
	v_mul_f32_e32 v49, v49, v49
	v_mul_f32_e32 v50, v50, v50
	v_mul_f32_e32 v51, v51, v51
	v_cvt_pk_bf16_f32 v48, v52, v48
	v_max_f32_e32 v40, 0, v40
	v_max_f32_e32 v41, 0, v41
	v_max_f32_e32 v42, 0, v42
	v_cvt_pk_bf16_f32 v49, v49, v50
	v_cvt_pk_bf16_f32 v50, v56, v53
	v_cvt_pk_bf16_f32 v51, v54, v51
	ds_write_b128 v220, v[48:51]
	ds_read_b128 v[236:239], v221
	v_mov_b64_e32 v[242:243], v[60:61]
	v_lshl_add_u64 v[242:243], v[242:243], 0, s[98:99]
	s_waitcnt lgkmcnt(2)
	global_store_dwordx4 v[240:241], v[232:235], off
	s_nop 1
	v_mul_f32_e32 v48, v40, v40
	v_max_f32_e32 v40, v45, v45
	v_mul_f32_e32 v45, v41, v41
	v_max_f32_e32 v41, v46, v46
	v_mul_f32_e32 v46, v42, v42
	v_max_f32_e32 v42, v47, v47
	v_max_f32_e32 v40, 0, v40
	v_max_f32_e32 v41, 0, v41
	v_max_f32_e32 v42, 0, v42
	v_max_f32_e32 v43, 0, v43
	v_max_f32_e32 v44, 0, v44
	v_mul_f32_e32 v40, v40, v40
	v_mul_f32_e32 v41, v41, v41
	v_mul_f32_e32 v42, v42, v42
	v_mul_f32_e32 v43, v43, v43
	v_mul_f32_e32 v44, v44, v44
	v_cvt_pk_bf16_f32 v40, v44, v40
	v_cvt_pk_bf16_f32 v41, v41, v42
	v_cvt_pk_bf16_f32 v42, v48, v45
	v_cvt_pk_bf16_f32 v43, v46, v43
	v_add_co_u32_e32 v46, vcc, s68, v120
	s_nop 0
	v_addc_co_u32_e32 v47, vcc, 0, v121, vcc
	v_max_f32_e32 v32, 0, v32
	ds_write_b128 v220, v[40:43]
	ds_read_b128 v[232:235], v221
	v_mov_b64_e32 v[240:241], v[46:47]
	s_waitcnt lgkmcnt(2)
; __device__ __forceinline__ u32x4 pack8(const f32x4& a, const f32x4& b) { u32x4 w; w.x = cvt_pk_bf16(a[0], a[1]); w.y = cvt_pk_bf16(a[2], a[3]); w.z = cvt_pk_bf16(b[0], b[1]); w.w = cvt_pk_bf16(b[2], b[3]); return w; }
; __device__ __forceinline__ float frsq(float x) { return __builtin_amdgcn_rsqf(x); }
; template <class Epi, bool ALIGN_EPI, bool SP2>
; __device__ __forceinline__ void gemm_phase(LAS unsigned char* lds, const int K, const Sched& S, const Epi& E) {
;     ...
;         if (!has_next) break;
; #pragma unroll
;         for (int a = 0; a < 2; ++a)
; #pragma unroll
;             for (int b = 0; b < 2; ++b)
; #pragma unroll
;                 for (int m = 0; m < 4; ++m)
; #pragma unroll
;                     for (int n = 0; n < 2; ++n) acc[a][b][m][n] = (f32x4){0.f, 0.f, 0.f, 0.f};
;         cur = nxt; cA = nA; cB = nB; ++ui;
;     __device__ __forceinline__ void operator()(Acc& acc, const Unit& u, int wr, int wc, int fr, int fq) const {
;     ...
;             for (int m = 0; m < 4; ++m) { const int row = row0 + ai * HALF + m * 16; const float rstd = (ACT == 0) ? frsq(ssv[ai][m] * (1.0f / D) + EPS) : 1.0f;
; #pragma unroll
;                 for (int bj = 0; bj < 2; ++bj) { f32x4 a = acc[ai][bj][m][0] * rstd, b = acc[ai][bj][m][1] * rstd;
;                     if (ACT == 1) {
; #pragma unroll
;                         for (int i = 0; i < 4; ++i) { const float x = fmaxf(a[i], 0.f), y = fmaxf(b[i], 0.f); a[i] = x * x; b[i] = y * y; } }
;                     *(u32x4*)(O + (size_t)row * ldc + col0 + bj * HALF) = pack8(a, b); }
	global_store_dwordx4 v[242:243], v[236:239], off
	v_max_f32_e32 v33, 0, v33
	v_max_f32_e32 v34, 0, v34
	v_mul_f32_e32 v40, v32, v32
	v_max_f32_e32 v32, v37, v37
	v_max_f32_e32 v32, 0, v32
	v_mul_f32_e32 v37, v33, v33
	v_max_f32_e32 v33, v38, v38
	v_mul_f32_e32 v38, v34, v34
	v_max_f32_e32 v34, v39, v39
	v_max_f32_e32 v36, 0, v36
	v_mul_f32_e32 v32, v32, v32
	v_max_f32_e32 v33, 0, v33
	v_max_f32_e32 v34, 0, v34
	v_max_f32_e32 v35, 0, v35
	v_lshl_add_u64 v[44:45], v[120:121], 0, s[24:25]
	v_mul_f32_e32 v36, v36, v36
	v_mul_f32_e32 v33, v33, v33
	v_mul_f32_e32 v34, v34, v34
	v_mul_f32_e32 v35, v35, v35
	v_cvt_pk_bf16_f32 v32, v36, v32
	v_max_f32_e32 v24, 0, v24
	v_max_f32_e32 v25, 0, v25
	v_max_f32_e32 v26, 0, v26
	v_cvt_pk_bf16_f32 v33, v33, v34
	v_cvt_pk_bf16_f32 v34, v40, v37
	v_cvt_pk_bf16_f32 v35, v38, v35
	ds_write_b128 v220, v[32:35]
	ds_read_b128 v[236:239], v221
	v_mov_b64_e32 v[242:243], v[44:45]
	v_lshl_add_u64 v[242:243], v[242:243], 0, s[98:99]
	s_waitcnt lgkmcnt(2)
	global_store_dwordx4 v[240:241], v[232:235], off
	s_nop 1
	v_mul_f32_e32 v32, v24, v24
	v_max_f32_e32 v24, v29, v29
	v_mul_f32_e32 v29, v25, v25
	v_max_f32_e32 v25, v30, v30
	v_mul_f32_e32 v30, v26, v26
	v_max_f32_e32 v26, v31, v31
	v_max_f32_e32 v24, 0, v24
	v_max_f32_e32 v25, 0, v25
	v_max_f32_e32 v26, 0, v26
	v_max_f32_e32 v27, 0, v27
	v_max_f32_e32 v28, 0, v28
	v_mul_f32_e32 v24, v24, v24
	v_mul_f32_e32 v25, v25, v25
	v_mul_f32_e32 v26, v26, v26
	v_mul_f32_e32 v27, v27, v27
	v_mul_f32_e32 v28, v28, v28
	v_cvt_pk_bf16_f32 v24, v28, v24
	v_cvt_pk_bf16_f32 v25, v25, v26
	v_cvt_pk_bf16_f32 v26, v32, v29
	v_cvt_pk_bf16_f32 v27, v30, v27
	v_add_co_u32_e32 v30, vcc, s69, v120
	s_nop 0
	v_addc_co_u32_e32 v31, vcc, 0, v121, vcc
	v_max_f32_e32 v16, 0, v16
	ds_write_b128 v220, v[24:27]
	ds_read_b128 v[232:235], v221
	v_mov_b64_e32 v[240:241], v[30:31]
	s_waitcnt lgkmcnt(2)
	global_store_dwordx4 v[242:243], v[236:239], off
	v_max_f32_e32 v17, 0, v17
	v_max_f32_e32 v18, 0, v18
	v_mul_f32_e32 v24, v16, v16
	v_max_f32_e32 v16, v21, v21
	v_max_f32_e32 v16, 0, v16
	v_mul_f32_e32 v21, v17, v17
	v_max_f32_e32 v17, v22, v22
	v_mul_f32_e32 v22, v18, v18
	v_max_f32_e32 v18, v23, v23
	v_max_f32_e32 v20, 0, v20
	v_mul_f32_e32 v16, v16, v16
	v_max_f32_e32 v17, 0, v17
	v_max_f32_e32 v18, 0, v18
	v_max_f32_e32 v19, 0, v19
	v_lshl_add_u64 v[28:29], v[120:121], 0, s[26:27]
	v_mul_f32_e32 v20, v20, v20
	v_mul_f32_e32 v17, v17, v17
	v_mul_f32_e32 v18, v18, v18
	v_mul_f32_e32 v19, v19, v19
	v_cvt_pk_bf16_f32 v16, v20, v16
	v_max_f32_e32 v8, 0, v8
	v_max_f32_e32 v9, 0, v9
	v_max_f32_e32 v10, 0, v10
	v_cvt_pk_bf16_f32 v17, v17, v18
	v_cvt_pk_bf16_f32 v18, v24, v21
	v_cvt_pk_bf16_f32 v19, v22, v19
	ds_write_b128 v220, v[16:19]
	ds_read_b128 v[236:239], v221
	v_mov_b64_e32 v[242:243], v[28:29]
	v_lshl_add_u64 v[242:243], v[242:243], 0, s[98:99]
	s_waitcnt lgkmcnt(2)
	global_store_dwordx4 v[240:241], v[232:235], off
	s_nop 1
	v_mul_f32_e32 v16, v8, v8
	v_max_f32_e32 v8, v13, v13
	v_mul_f32_e32 v13, v9, v9
	v_max_f32_e32 v9, v14, v14
	v_mul_f32_e32 v14, v10, v10
	v_max_f32_e32 v10, v15, v15
	v_max_f32_e32 v8, 0, v8
	v_max_f32_e32 v9, 0, v9
	v_max_f32_e32 v10, 0, v10
	v_max_f32_e32 v11, 0, v11
	v_max_f32_e32 v12, 0, v12
	v_mul_f32_e32 v8, v8, v8
	v_mul_f32_e32 v9, v9, v9
	v_mul_f32_e32 v10, v10, v10
	v_mul_f32_e32 v11, v11, v11
	v_mul_f32_e32 v12, v12, v12
	v_cvt_pk_bf16_f32 v8, v12, v8
	v_cvt_pk_bf16_f32 v9, v9, v10
	v_cvt_pk_bf16_f32 v10, v16, v13
	v_cvt_pk_bf16_f32 v11, v14, v11
	v_add_co_u32_e32 v14, vcc, s70, v120
	v_addc_co_u32_e32 v15, vcc, 0, v121, vcc
	v_max_f32_e32 v0, 0, v0
	v_max_f32_e32 v1, 0, v1
	v_max_f32_e32 v2, 0, v2
	ds_write_b128 v220, v[8:11]
	ds_read_b128 v[232:235], v221
	v_mov_b64_e32 v[240:241], v[14:15]
	s_waitcnt lgkmcnt(2)
	global_store_dwordx4 v[242:243], v[236:239], off
	s_nop 1
	v_mul_f32_e32 v8, v0, v0
	v_max_f32_e32 v0, v5, v5
	v_mul_f32_e32 v5, v1, v1
	v_max_f32_e32 v1, v6, v6
	v_mul_f32_e32 v6, v2, v2
	v_max_f32_e32 v2, v7, v7
	v_max_f32_e32 v0, 0, v0
	v_max_f32_e32 v1, 0, v1
	v_max_f32_e32 v2, 0, v2
	v_max_f32_e32 v3, 0, v3
	v_lshl_add_u64 v[12:13], v[120:121], 0, s[28:29]
	v_max_f32_e32 v4, 0, v4
	v_mul_f32_e32 v0, v0, v0
	v_mul_f32_e32 v1, v1, v1
	v_mul_f32_e32 v2, v2, v2
	v_mul_f32_e32 v3, v3, v3
	s_andn2_b64 vcc, exec, s[38:39]
	s_mov_b64 s[38:39], -1
	v_mul_f32_e32 v4, v4, v4
	v_cvt_pk_bf16_f32 v0, v4, v0
	v_cvt_pk_bf16_f32 v1, v1, v2
	v_cvt_pk_bf16_f32 v2, v8, v5
	v_cvt_pk_bf16_f32 v3, v6, v3
	ds_write_b128 v220, v[0:3]
	ds_read_b128 v[236:239], v221
	v_mov_b64_e32 v[242:243], v[12:13]
	v_lshl_add_u64 v[242:243], v[242:243], 0, s[98:99]
	s_waitcnt lgkmcnt(2)
	global_store_dwordx4 v[240:241], v[232:235], off
	s_waitcnt lgkmcnt(0)
	global_store_dwordx4 v[242:243], v[236:239], off
	s_cbranch_vccnz .LBB0_1084
	s_andn2_b64 vcc, exec, s[10:11]
	s_cbranch_vccnz .LBB0_1083
	s_barrier
	s_branch .LBB0_1083

; #define PG8_STAGE(bufoff, gbase, voff) do { _Pragma("unroll") for (int _i = 0; _i < 2; ++_i) \
;         __builtin_amdgcn_global_load_lds((const unsigned*)((const char*)(gbase) + (voff)[_i]), (LAS unsigned*)(lds + (bufoff) + ldsw + _i * 8192), 16, 0, 0); } while (0)
; #define PG8_WAIT_V(n) asm volatile("s_waitcnt vmcnt(" #n ")" ::: "memory")
; #define PG8_BAR __builtin_amdgcn_s_barrier()
; template <class Epi, bool ALIGN_EPI, bool SP2>
; __device__ __forceinline__ void gemm_phase(LAS unsigned char* lds, const int K, const Sched& S, const Epi& E) {
;     ...
;     for (int i = 0; i < 2; ++i) { int R, C; stage_rc(tid * 16 + i * 8192, R, C); const int Rb = (R & ~31) + perm32(R & 31);
;         voffA[i] = (unsigned)(R * K + C) * 2u; voffB[i] = (unsigned)(Rb * K + C) * 2u; }
;     const size_t kstep = (size_t)(BK * 2);
;     const size_t hstep = (size_t)HALF * K * 2;
;     ...
;         PG8_STAGE(PG8_SB(0, 0), cB, voffB); PG8_STAGE(PG8_SB(0, 1), cB + hstep, voffB); PG8_STAGE(PG8_SA(0, 0), cA, voffA); PG8_STAGE(PG8_SA(0, 1), cA + hstep, voffA);
;         if (wr == 1) PG8_BAR;
;         PG8_WAIT_V(2); PG8_BAR;
;         PG8_STAGE(PG8_SB(1, 0), cB + kstep, voffB); PG8_STAGE(PG8_SA(1, 0), cA + kstep, voffA); PG8_STAGE(PG8_SB(1, 1), cB + hstep + kstep, voffB);
;         PG8_WAIT_V(6); PG8_BAR;
.LBB0_1169:
	s_cmp_lt_i32 s82, 9
	s_cselect_b64 s[2:3], -1, 0
	s_and_b64 s[2:3], s[2:3], s[6:7]
	s_andn2_b64 vcc, exec, s[2:3]
	s_cbranch_vccnz .LBB0_1186
	s_cmpk_gt_i32 s52, 0x1ff
	v_readfirstlane_b32 s10, v228
	s_cbranch_scc1 .LBB0_1186
	s_mov_b64 s[100:101], 0x8000
	v_lshrrev_b32_e32 v0, 5, v228
	v_lshrrev_b32_e32 v2, 1, v228
	v_and_b32_e32 v0, 4, v0
	s_waitcnt lgkmcnt(0)
	v_bfe_u32 v1, v228, 2, 2
	v_and_b32_e32 v2, 24, v2
	v_or3_b32 v0, v0, v1, v2
	v_lshlrev_b32_e32 v1, 4, v228
	v_add_u32_e32 v8, 0x2000, v1
	v_lshrrev_b32_e32 v2, 7, v8
	s_movk_i32 s2, 0xe0
	v_and_b32_e32 v4, 32, v228
	v_and_or_b32 v3, v2, s2, v0
	v_bitop3_b32 v9, v1, v4, 48 bitop3:0x6c
	v_and_b32_e32 v10, 64, v228
	v_bfe_u32 v11, v228, 2, 4
	s_movk_i32 s2, 0xf0
	s_add_u32 s28, s92, 0xf000000
	v_or_b32_e32 v1, v9, v10
	v_and_or_b32 v2, v2, s2, v11
	s_addc_u32 s29, s93, 0
	v_lshl_or_b32 v178, v2, 7, v1
	v_lshrrev_b32_e32 v2, 3, v228
	s_movk_i32 s2, 0x60
	s_add_u32 s30, s92, 0x1580000
	v_and_or_b32 v0, v2, s2, v0
	s_movk_i32 s2, 0x70
	s_addc_u32 s31, s93, 0
	v_lshl_or_b32 v180, v0, 13, v1
	v_and_or_b32 v0, v2, s2, v11
	s_lshl_b32 s2, s52, 6
	s_and_b32 s2, s2, 0x1c0
	s_ashr_i32 s3, s52, 3
	s_add_i32 s2, s2, s3
	s_lshr_b32 s2, s2, 2
	s_and_b32 s2, s2, 0x3ffffff8
	s_and_b32 s4, s3, 7
	s_lshr_b32 s8, s10, 6
	s_or_b32 s2, s2, s4
	s_bfe_u32 s45, s3, 0x20003
	s_mov_b32 s3, 0
	s_lshr_b32 s9, s10, 8
	s_lshl_b32 s34, s8, 10
	s_lshl_b64 s[4:5], s[2:3], 21
	s_lshl_b32 s6, s45, 21
	s_add_u32 s24, s30, s6
	s_addc_u32 s25, s31, 0
	s_add_i32 s35, s34, 0
	s_add_i32 m0, s35, 0x10000
	v_lshl_or_b32 v176, v3, 13, v1
	global_load_lds_dwordx4 v180, s[24:25]
	s_add_i32 m0, s35, 0x12000
	s_add_u32 s6, s24, 0x100000
	global_load_lds_dwordx4 v176, s[24:25]
	s_addc_u32 s7, s25, 0
	s_add_i32 m0, s35, 0x14000
	v_lshl_or_b32 v182, v0, 7, v1
	global_load_lds_dwordx4 v180, s[6:7]
	s_add_i32 m0, s35, 0x16000
	s_add_u32 s22, s28, s4
	s_addc_u32 s23, s29, s5
	s_add_i32 s36, s35, 0x2000
	global_load_lds_dwordx4 v176, s[6:7]
	s_mov_b32 m0, s35
	s_add_u32 s4, s22, 0x4000
	global_load_lds_dwordx4 v182, s[22:23]
	s_mov_b32 m0, s36
	s_addc_u32 s5, s23, 0
	s_add_i32 s37, s35, 0x4000
	global_load_lds_dwordx4 v178, s[22:23]
	s_mov_b32 m0, s37
	s_add_i32 s38, s35, 0x6000
	global_load_lds_dwordx4 v182, s[4:5]
	s_mov_b32 m0, s38
	v_mov_b32_e32 v181, 0
	global_load_lds_dwordx4 v178, s[4:5]
	v_mov_b32_e32 v177, v181
	v_mov_b32_e32 v183, v181
	v_mov_b32_e32 v179, v181
	s_cmp_eq_u32 s9, 1
	v_lshl_add_u64 v[6:7], s[24:25], 0, v[180:181]
	v_lshl_add_u64 v[4:5], s[24:25], 0, v[176:177]
	v_lshl_add_u64 v[0:1], s[22:23], 0, v[182:183]
	s_cselect_b64 s[4:5], -1, 0
	s_cmp_lg_u32 s9, 1
	v_lshl_add_u64 v[2:3], s[22:23], 0, v[178:179]
	s_cbranch_scc1 .LBB0_1173
	s_barrier
.LBB0_1173:
	s_add_u32 s6, s92, 0x3000000
	s_addc_u32 s7, s93, 0
	s_lshl_b32 s8, s8, 5
	s_lshl_b32 s39, s9, 6
	s_lshl_b32 s11, s9, 13
	s_and_b32 s40, s8, 0x60
	s_mov_b64 s[8:9], 0x80
	s_add_i32 m0, s35, 0x18000
	v_lshl_add_u64 v[6:7], v[6:7], 0, s[8:9]
	s_lshl_b32 s14, s40, 7
	s_waitcnt vmcnt(2)
	s_barrier
	global_load_lds_dwordx4 v[6:7], off
	v_lshl_add_u64 v[4:5], v[4:5], 0, s[8:9]
	s_add_i32 m0, s35, 0x1a000
	s_add_i32 s41, s35, 0x8000
	s_add_i32 s42, s35, 0xa000
	global_load_lds_dwordx4 v[4:5], off
	v_lshl_add_u64 v[0:1], v[0:1], 0, s[100:101]
	s_mov_b32 m0, s41
	s_add_u32 s12, s24, 0x100080
	global_load_lds_dwordx4 v[0:1], off
	v_lshl_add_u64 v[0:1], v[2:3], 0, s[100:101]
	s_mov_b32 m0, s42
	s_addc_u32 s13, s25, 0
	global_load_lds_dwordx4 v[0:1], off
	s_add_i32 m0, s35, 0x1c000
	v_lshl_add_u64 v[0:1], s[12:13], 0, v[180:181]
	global_load_lds_dwordx4 v[0:1], off
	v_lshl_add_u64 v[0:1], s[12:13], 0, v[176:177]
	s_add_i32 m0, s35, 0x1e000
	v_bfe_u32 v201, v228, 4, 2
	global_load_lds_dwordx4 v[0:1], off
	v_and_b32_e32 v200, 15, v228
	v_lshlrev_b32_e32 v0, 4, v201
	v_lshlrev_b32_e32 v2, 2, v228
	v_lshl_or_b32 v1, v200, 6, v0
	v_and_b32_e32 v2, 32, v2
	v_bitop3_b32 v1, v1, s11, v2 bitop3:0xde
	v_lshlrev_b32_e32 v3, 6, v228
	s_movk_i32 s11, 0x3c0
	v_and_or_b32 v0, v3, s11, v0
	v_bitop3_b32 v202, s14, v0, v2 bitop3:0xf6
	v_lshlrev_b32_e32 v0, 10, v228
	v_and_b32_e32 v0, 0xe0000, v0
	v_lshrrev_b32_e32 v0, 6, v0
	v_lshlrev_b32_e32 v2, 7, v11
	v_or3_b32 v0, v9, v0, v2
	v_add_u32_e32 v184, v0, v10
	v_lshlrev_b32_e32 v0, 6, v8
	s_waitcnt vmcnt(6)
	s_cmpk_lt_u32 s10, 0x100
	v_and_b32_e32 v0, 0x1e0000, v0
	v_lshrrev_b32_e32 v0, 6, v0
	s_cselect_b64 s[10:11], -1, 0
	v_or3_b32 v0, v9, v0, v2
	s_add_i32 s43, 0, 0x10000
	s_add_i32 s44, 0, 0x14000
	v_mov_b32_e32 v185, v181
	v_add_u32_e32 v186, v0, v10
	v_mov_b32_e32 v187, v181
	v_add_u32_e32 v203, s43, v202
	v_add_u32_e32 v204, s44, v202
	v_add_u32_e32 v205, 0, v1
	v_mov_b32_e32 v206, 0x358637bd
	s_barrier
	s_branch .LBB0_1176

;     __device__ __forceinline__ const char* aptr(const Unit& u) const { return (u.kind == 1 ? A1 : A0) + (size_t)u.pm * tstep; }
;     __device__ __forceinline__ const char* bptr(const Unit& u) const { return (u.kind == 1 ? B1 : B0) + (size_t)u.pn * tstep; }
; #define PG8_STAGE(bufoff, gbase, voff) do { _Pragma("unroll") for (int _i = 0; _i < 2; ++_i) \
;         __builtin_amdgcn_global_load_lds((const unsigned*)((const char*)(gbase) + (voff)[_i]), (LAS unsigned*)(lds + (bufoff) + ldsw + _i * 8192), 16, 0, 0); } while (0)
; #define PG8_LDA(dst, b, h) do { _Pragma("unroll") for (int m = 0; m < 4; ++m) _Pragma("unroll") for (int k = 0; k < 2; ++k) dst[m][k] = *(const LAS bf16x8*)(lds + PG8_SA(b, h) + aoff + m * 2048 + k * 1024); } while (0)
; #define PG8_LDB(dst, b, h) do { _Pragma("unroll") for (int n = 0; n < 2; ++n) _Pragma("unroll") for (int k = 0; k < 2; ++k) dst[n][k] = *(const LAS bf16x8*)(lds + PG8_SB(b, h) + boff + n * 2048 + k * 1024); } while (0)
; #define PG8_WAIT_V(n) asm volatile("s_waitcnt vmcnt(" #n ")" ::: "memory")
; #define PG8_WAIT_L(n) asm volatile("s_waitcnt lgkmcnt(" #n ")" ::: "memory")
; #define PG8_BAR __builtin_amdgcn_s_barrier()
; template <class Epi, bool ALIGN_EPI, bool SP2>
; __device__ __forceinline__ void gemm_phase(LAS unsigned char* lds, const int K, const Sched& S, const Epi& E) {
;     ...
;         const bool has_next = S.next(ui + 1, nxt);
;         const char* nA = has_next ? S.aptr(nxt) : cA; const char* nB = has_next ? S.bptr(nxt) : cB;
;         for (int t = 0; t < nt; t += 2) {
;             const bool last = (t == nt - 2);
;             const char* a1 = cA + (size_t)(t + 1) * kstep;
;             const char* a2 = last ? nA : cA + (size_t)(t + 2) * kstep; const char* b2 = last ? nB : cB + (size_t)(t + 2) * kstep;
;             const char* a3 = a2 + kstep; const char* b3 = b2 + kstep;
;             if constexpr (SP2) {
;             PG8_LDB(B0, 0, 0); PG8_LDB(B1, 0, 1); PG8_SCHED; PG8_LDA(At, 0, 0); PG8_STAGE(PG8_SA(1, 1), a1 + hstep, voffA);
;             PG8_WAIT_V(8); PG8_WAIT_L(0); PG8_BAR; PG8_MMA(0, 0, At, B0); PG8_MMA(0, 1, At, B1); PG8_BAR; PG8_SCHED;
;             PG8_LDA(At, 0, 1); PG8_STAGE(PG8_SB(0, 0), b2, voffB); PG8_STAGE(PG8_SB(0, 1), b2 + hstep, voffB); PG8_STAGE(PG8_SA(0, 0), a2, voffA);
;             PG8_WAIT_V(8); PG8_WAIT_L(0); PG8_BAR; PG8_MMA(1, 0, At, B0); PG8_MMA(1, 1, At, B1); PG8_BAR; PG8_SCHED;
.LBB0_1178:
	s_ashr_i32 s13, s12, 31
	s_lshl_b64 s[16:17], s[12:13], 21
	s_add_u32 s16, s28, s16
	s_addc_u32 s17, s29, s17
	s_and_b64 s[20:21], s[18:19], exec
	s_cselect_b32 s13, s17, s23
	s_cselect_b32 s46, s16, s22
	s_ashr_i32 s15, s14, 31
	s_lshl_b64 s[20:21], s[14:15], 21
	s_add_u32 s20, s30, s20
	s_addc_u32 s21, s31, s21
	s_and_b64 s[26:27], s[18:19], exec
	s_cselect_b32 s15, s21, s25
	s_cselect_b32 s47, s20, s24
	s_add_u32 s22, s22, 0xc000
	s_addc_u32 s23, s23, 0
	s_add_u32 s48, s24, 0x100
	v_mov_b64_e32 v[0:1], 0
	v_mov_b64_e32 v[2:3], 0
	v_mov_b64_e32 v[4:5], 0
	v_mov_b64_e32 v[6:7], 0
	v_mov_b64_e32 v[8:9], 0
	v_mov_b64_e32 v[10:11], 0
	v_mov_b64_e32 v[12:13], 0
	v_mov_b64_e32 v[14:15], 0
	v_mov_b64_e32 v[16:17], 0
	v_mov_b64_e32 v[18:19], 0
	v_mov_b64_e32 v[20:21], 0
	v_mov_b64_e32 v[22:23], 0
	v_mov_b64_e32 v[24:25], 0
	v_mov_b64_e32 v[26:27], 0
	v_mov_b64_e32 v[28:29], 0
	v_mov_b64_e32 v[30:31], 0
	v_mov_b64_e32 v[32:33], 0
	v_mov_b64_e32 v[34:35], 0
	v_mov_b64_e32 v[36:37], 0
	v_mov_b64_e32 v[38:39], 0
	v_mov_b64_e32 v[40:41], 0
	v_mov_b64_e32 v[42:43], 0
	v_mov_b64_e32 v[44:45], 0
	v_mov_b64_e32 v[46:47], 0
	v_mov_b64_e32 v[48:49], 0
	v_mov_b64_e32 v[50:51], 0
	v_mov_b64_e32 v[52:53], 0
	v_mov_b64_e32 v[54:55], 0
	v_mov_b64_e32 v[56:57], 0
	v_mov_b64_e32 v[58:59], 0
	v_mov_b64_e32 v[60:61], 0
	v_mov_b64_e32 v[62:63], 0
	v_mov_b64_e32 v[64:65], 0
	v_mov_b64_e32 v[66:67], 0
	v_mov_b64_e32 v[68:69], 0
	v_mov_b64_e32 v[70:71], 0
	v_mov_b64_e32 v[72:73], 0
	v_mov_b64_e32 v[74:75], 0
	v_mov_b64_e32 v[76:77], 0
	v_mov_b64_e32 v[78:79], 0
	v_mov_b64_e32 v[80:81], 0
	v_mov_b64_e32 v[82:83], 0
	v_mov_b64_e32 v[84:85], 0
	v_mov_b64_e32 v[86:87], 0
	v_mov_b64_e32 v[88:89], 0
	v_mov_b64_e32 v[90:91], 0
	v_mov_b64_e32 v[92:93], 0
	v_mov_b64_e32 v[94:95], 0
	v_mov_b64_e32 v[96:97], 0
	v_mov_b64_e32 v[98:99], 0
	v_mov_b64_e32 v[100:101], 0
	v_mov_b64_e32 v[102:103], 0
	v_mov_b64_e32 v[104:105], 0
	v_mov_b64_e32 v[106:107], 0
	v_mov_b64_e32 v[108:109], 0
	v_mov_b64_e32 v[110:111], 0
	v_mov_b64_e32 v[112:113], 0
	v_mov_b64_e32 v[114:115], 0
	v_mov_b64_e32 v[116:117], 0
	v_mov_b64_e32 v[118:119], 0
	v_mov_b64_e32 v[120:121], 0
	v_mov_b64_e32 v[122:123], 0
	v_mov_b64_e32 v[124:125], 0
	v_mov_b64_e32 v[126:127], 0
	s_addc_u32 s49, s25, 0
	s_mov_b32 s50, -2
.LBB0_1179:
	ds_read_b128 v[128:131], v203
	ds_read_b128 v[132:135], v203 offset:1024
	ds_read_b128 v[136:139], v203 offset:2048
	ds_read_b128 v[140:143], v203 offset:3072
	ds_read_b128 v[144:147], v204
	ds_read_b128 v[148:151], v204 offset:1024
	ds_read_b128 v[152:155], v204 offset:2048
	ds_read_b128 v[156:159], v204 offset:3072
	s_add_u32 s24, s22, 0x4000
	s_addc_u32 s25, s23, 0
	s_cmp_eq_u32 s50, 60
	s_cselect_b32 s27, s13, s25
	s_cselect_b32 s26, s46, s24
	s_cselect_b32 s25, s15, s49
	s_cselect_b32 s24, s47, s48
	v_lshl_add_u64 v[212:213], s[22:23], 0, v[184:185]
	s_add_i32 m0, s35, 0xc000
	ds_read_b128 v[160:163], v205
	ds_read_b128 v[164:167], v205 offset:1024
	ds_read_b128 v[168:171], v205 offset:2048
	ds_read_b128 v[172:175], v205 offset:3072
	ds_read_b128 v[188:191], v205 offset:4096
	ds_read_b128 v[192:195], v205 offset:5120
	ds_read_b128 v[196:199], v205 offset:6144
	ds_read_b128 v[208:211], v205 offset:7168
	global_load_lds_dwordx4 v[212:213], off
	v_lshl_add_u64 v[212:213], s[22:23], 0, v[186:187]
	s_add_i32 m0, s35, 0xe000
	s_nop 0
	global_load_lds_dwordx4 v[212:213], off
	s_waitcnt vmcnt(8)
	s_waitcnt lgkmcnt(0)
	s_setprio 1
	s_waitcnt lgkmcnt(0)
	v_mfma_f32_16x16x32_bf16 v[124:127], v[128:131], v[160:163], v[124:127]
	v_mfma_f32_16x16x32_bf16 v[120:123], v[136:139], v[160:163], v[120:123]
	v_mfma_f32_16x16x32_bf16 v[112:115], v[128:131], v[168:171], v[112:115]
	v_mfma_f32_16x16x32_bf16 v[104:107], v[136:139], v[168:171], v[104:107]
	s_barrier
	v_mfma_f32_16x16x32_bf16 v[96:99], v[128:131], v[188:191], v[96:99]
	v_mfma_f32_16x16x32_bf16 v[88:91], v[136:139], v[188:191], v[88:91]
	v_mfma_f32_16x16x32_bf16 v[80:83], v[128:131], v[196:199], v[80:83]
	v_mfma_f32_16x16x32_bf16 v[72:75], v[136:139], v[196:199], v[72:75]
	v_mfma_f32_16x16x32_bf16 v[124:127], v[132:135], v[164:167], v[124:127]
	v_mfma_f32_16x16x32_bf16 v[120:123], v[140:143], v[164:167], v[120:123]
	v_mfma_f32_16x16x32_bf16 v[112:115], v[132:135], v[172:175], v[112:115]
	v_mfma_f32_16x16x32_bf16 v[104:107], v[140:143], v[172:175], v[104:107]
	v_mfma_f32_16x16x32_bf16 v[96:99], v[132:135], v[192:195], v[96:99]
	v_mfma_f32_16x16x32_bf16 v[88:91], v[140:143], v[192:195], v[88:91]
	v_mfma_f32_16x16x32_bf16 v[80:83], v[132:135], v[208:211], v[80:83]
	v_mfma_f32_16x16x32_bf16 v[72:75], v[140:143], v[208:211], v[72:75]
	s_setprio 0
	s_setprio 1
	v_mfma_f32_16x16x32_bf16 v[116:119], v[144:147], v[160:163], v[116:119]
	v_mfma_f32_16x16x32_bf16 v[108:111], v[152:155], v[160:163], v[108:111]
	v_mfma_f32_16x16x32_bf16 v[100:103], v[144:147], v[168:171], v[100:103]
	v_mfma_f32_16x16x32_bf16 v[92:95], v[152:155], v[168:171], v[92:95]
	v_mfma_f32_16x16x32_bf16 v[84:87], v[144:147], v[188:191], v[84:87]
	v_mfma_f32_16x16x32_bf16 v[76:79], v[152:155], v[188:191], v[76:79]
	v_mfma_f32_16x16x32_bf16 v[68:71], v[144:147], v[196:199], v[68:71]
	v_mfma_f32_16x16x32_bf16 v[64:67], v[152:155], v[196:199], v[64:67]
	v_mfma_f32_16x16x32_bf16 v[116:119], v[148:151], v[164:167], v[116:119]
	v_mfma_f32_16x16x32_bf16 v[108:111], v[156:159], v[164:167], v[108:111]
	v_mfma_f32_16x16x32_bf16 v[100:103], v[148:151], v[172:175], v[100:103]
	v_mfma_f32_16x16x32_bf16 v[92:95], v[156:159], v[172:175], v[92:95]
	v_mfma_f32_16x16x32_bf16 v[84:87], v[148:151], v[192:195], v[84:87]
	v_mfma_f32_16x16x32_bf16 v[76:79], v[156:159], v[192:195], v[76:79]
	v_mfma_f32_16x16x32_bf16 v[68:71], v[148:151], v[208:211], v[68:71]
	v_mfma_f32_16x16x32_bf16 v[64:67], v[156:159], v[208:211], v[64:67]
	s_setprio 0
	s_barrier
; #define PG8_STAGE(bufoff, gbase, voff) do { _Pragma("unroll") for (int _i = 0; _i < 2; ++_i) \
;         __builtin_amdgcn_global_load_lds((const unsigned*)((const char*)(gbase) + (voff)[_i]), (LAS unsigned*)(lds + (bufoff) + ldsw + _i * 8192), 16, 0, 0); } while (0)
; #define PG8_LDA(dst, b, h) do { _Pragma("unroll") for (int m = 0; m < 4; ++m) _Pragma("unroll") for (int k = 0; k < 2; ++k) dst[m][k] = *(const LAS bf16x8*)(lds + PG8_SA(b, h) + aoff + m * 2048 + k * 1024); } while (0)
; #define PG8_LDB(dst, b, h) do { _Pragma("unroll") for (int n = 0; n < 2; ++n) _Pragma("unroll") for (int k = 0; k < 2; ++k) dst[n][k] = *(const LAS bf16x8*)(lds + PG8_SB(b, h) + boff + n * 2048 + k * 1024); } while (0)
; #define PG8_MMA(ai, bj, At, Bt) do { __builtin_amdgcn_s_setprio(1); _Pragma("unroll") for (int m = 0; m < 4; ++m) _Pragma("unroll") for (int n = 0; n < 2; ++n) _Pragma("unroll") for (int k = 0; k < 2; ++k) \
;         acc[ai][bj][m][n] = __builtin_amdgcn_mfma_f32_16x16x32_bf16(Bt[n][k], At[m][k], acc[ai][bj][m][n], 0, 0, 0); __builtin_amdgcn_s_setprio(0); } while (0)
; #define PG8_WAIT_V(n) asm volatile("s_waitcnt vmcnt(" #n ")" ::: "memory")
; #define PG8_WAIT_L(n) asm volatile("s_waitcnt lgkmcnt(" #n ")" ::: "memory")
; #define PG8_BAR __builtin_amdgcn_s_barrier()
; template <class Epi, bool ALIGN_EPI, bool SP2>
; __device__ __forceinline__ void gemm_phase(LAS unsigned char* lds, const int K, const Sched& S, const Epi& E) {
;     ...
;             PG8_LDB(B0, 0, 0); PG8_LDB(B1, 0, 1); PG8_SCHED; PG8_LDA(At, 0, 0); PG8_STAGE(PG8_SA(1, 1), a1 + hstep, voffA);
;             PG8_WAIT_V(8); PG8_WAIT_L(0); PG8_BAR; PG8_MMA(0, 0, At, B0); PG8_MMA(0, 1, At, B1); PG8_BAR; PG8_SCHED;
;             PG8_LDA(At, 0, 1); PG8_STAGE(PG8_SB(0, 0), b2, voffB); PG8_STAGE(PG8_SB(0, 1), b2 + hstep, voffB); PG8_STAGE(PG8_SA(0, 0), a2, voffA);
;             PG8_WAIT_V(8); PG8_WAIT_L(0); PG8_BAR; PG8_MMA(1, 0, At, B0); PG8_MMA(1, 1, At, B1); PG8_BAR; PG8_SCHED;
;             PG8_LDB(B0, 1, 0); PG8_LDB(B1, 1, 1); PG8_SCHED; PG8_LDA(At, 1, 0); PG8_STAGE(PG8_SA(0, 1), a2 + hstep, voffA);
;             PG8_WAIT_V(8); PG8_WAIT_L(0); PG8_BAR; PG8_MMA(0, 0, At, B0); PG8_MMA(0, 1, At, B1); PG8_BAR; PG8_SCHED;
;             PG8_LDA(At, 1, 1); PG8_STAGE(PG8_SB(1, 0), b3, voffB); PG8_STAGE(PG8_SB(1, 1), b3 + hstep, voffB); PG8_STAGE(PG8_SA(1, 0), a3, voffA);
	s_add_i32 s51, s43, s34
	v_lshl_add_u64 v[212:213], s[24:25], 0, v[180:181]
	s_mov_b32 m0, s51
	ds_read_b128 v[160:163], v205 offset:16384
	ds_read_b128 v[164:167], v205 offset:17408
	ds_read_b128 v[168:171], v205 offset:18432
	ds_read_b128 v[172:175], v205 offset:19456
	ds_read_b128 v[188:191], v205 offset:20480
	ds_read_b128 v[192:195], v205 offset:21504
	ds_read_b128 v[196:199], v205 offset:22528
	ds_read_b128 v[208:211], v205 offset:23552
	global_load_lds_dwordx4 v[212:213], off
	s_add_i32 m0, s51, 0x2000
	s_add_u32 s54, s24, 0x100000
	v_lshl_add_u64 v[214:215], s[24:25], 0, v[176:177]
	s_addc_u32 s55, s25, 0
	s_add_i32 s51, s44, s34
	global_load_lds_dwordx4 v[214:215], off
	v_lshl_add_u64 v[216:217], s[54:55], 0, v[180:181]
	s_mov_b32 m0, s51
	v_lshl_add_u64 v[218:219], s[26:27], 0, v[178:179]
	global_load_lds_dwordx4 v[216:217], off
	v_lshl_add_u64 v[216:217], s[54:55], 0, v[176:177]
	s_add_i32 m0, s51, 0x2000
	s_nop 0
	global_load_lds_dwordx4 v[216:217], off
	v_lshl_add_u64 v[216:217], s[26:27], 0, v[182:183]
	s_mov_b32 m0, s35
	s_nop 0
	global_load_lds_dwordx4 v[216:217], off
	s_mov_b32 m0, s36
	s_nop 0
	global_load_lds_dwordx4 v[218:219], off
	s_waitcnt vmcnt(8)
	s_waitcnt lgkmcnt(0)
	s_setprio 1
	s_waitcnt lgkmcnt(0)
	v_mfma_f32_16x16x32_bf16 v[60:63], v[128:131], v[160:163], v[60:63]
	v_mfma_f32_16x16x32_bf16 v[56:59], v[136:139], v[160:163], v[56:59]
	v_mfma_f32_16x16x32_bf16 v[48:51], v[128:131], v[168:171], v[48:51]
	v_mfma_f32_16x16x32_bf16 v[40:43], v[136:139], v[168:171], v[40:43]
	s_barrier
	v_mfma_f32_16x16x32_bf16 v[32:35], v[128:131], v[188:191], v[32:35]
	v_mfma_f32_16x16x32_bf16 v[24:27], v[136:139], v[188:191], v[24:27]
	v_mfma_f32_16x16x32_bf16 v[16:19], v[128:131], v[196:199], v[16:19]
	v_mfma_f32_16x16x32_bf16 v[8:11], v[136:139], v[196:199], v[8:11]
	v_mfma_f32_16x16x32_bf16 v[60:63], v[132:135], v[164:167], v[60:63]
	v_mfma_f32_16x16x32_bf16 v[56:59], v[140:143], v[164:167], v[56:59]
	v_mfma_f32_16x16x32_bf16 v[48:51], v[132:135], v[172:175], v[48:51]
	v_mfma_f32_16x16x32_bf16 v[40:43], v[140:143], v[172:175], v[40:43]
	v_mfma_f32_16x16x32_bf16 v[32:35], v[132:135], v[192:195], v[32:35]
	v_mfma_f32_16x16x32_bf16 v[24:27], v[140:143], v[192:195], v[24:27]
	v_mfma_f32_16x16x32_bf16 v[16:19], v[132:135], v[208:211], v[16:19]
	v_mfma_f32_16x16x32_bf16 v[8:11], v[140:143], v[208:211], v[8:11]
	s_setprio 0
	s_setprio 1
	v_mfma_f32_16x16x32_bf16 v[52:55], v[144:147], v[160:163], v[52:55]
	v_mfma_f32_16x16x32_bf16 v[44:47], v[152:155], v[160:163], v[44:47]
	v_mfma_f32_16x16x32_bf16 v[36:39], v[144:147], v[168:171], v[36:39]
	v_mfma_f32_16x16x32_bf16 v[28:31], v[152:155], v[168:171], v[28:31]
	v_mfma_f32_16x16x32_bf16 v[20:23], v[144:147], v[188:191], v[20:23]
	v_mfma_f32_16x16x32_bf16 v[12:15], v[152:155], v[188:191], v[12:15]
	v_mfma_f32_16x16x32_bf16 v[4:7], v[144:147], v[196:199], v[4:7]
	v_mfma_f32_16x16x32_bf16 v[0:3], v[152:155], v[196:199], v[0:3]
	v_mfma_f32_16x16x32_bf16 v[52:55], v[148:151], v[164:167], v[52:55]
	v_mfma_f32_16x16x32_bf16 v[44:47], v[156:159], v[164:167], v[44:47]
	v_mfma_f32_16x16x32_bf16 v[36:39], v[148:151], v[172:175], v[36:39]
	v_mfma_f32_16x16x32_bf16 v[28:31], v[156:159], v[172:175], v[28:31]
	v_mfma_f32_16x16x32_bf16 v[20:23], v[148:151], v[192:195], v[20:23]
	v_mfma_f32_16x16x32_bf16 v[12:15], v[156:159], v[192:195], v[12:15]
	v_mfma_f32_16x16x32_bf16 v[4:7], v[148:151], v[208:211], v[4:7]
	v_mfma_f32_16x16x32_bf16 v[0:3], v[156:159], v[208:211], v[0:3]
	s_setprio 0
	s_barrier
	s_add_i32 s51, 0, 0x18000
	s_add_i32 s53, 0, 0x1c000
	v_add_u32_e32 v140, s51, v202
	v_add_u32_e32 v156, s53, v202
	ds_read_b128 v[128:131], v140
	ds_read_b128 v[132:135], v140 offset:1024
	ds_read_b128 v[136:139], v140 offset:2048
	ds_read_b128 v[140:143], v140 offset:3072
	ds_read_b128 v[144:147], v156
	ds_read_b128 v[148:151], v156 offset:1024
	ds_read_b128 v[152:155], v156 offset:2048
	ds_read_b128 v[156:159], v156 offset:3072
	s_add_u32 s26, s26, 0x4000
	s_addc_u32 s27, s27, 0
	s_mov_b32 m0, s37
	v_lshl_add_u64 v[220:221], s[26:27], 0, v[182:183]
	ds_read_b128 v[160:163], v205 offset:32768
	ds_read_b128 v[164:167], v205 offset:33792
	ds_read_b128 v[168:171], v205 offset:34816
	ds_read_b128 v[172:175], v205 offset:35840
	ds_read_b128 v[188:191], v205 offset:36864
	ds_read_b128 v[192:195], v205 offset:37888
	ds_read_b128 v[196:199], v205 offset:38912
	ds_read_b128 v[208:211], v205 offset:39936
	global_load_lds_dwordx4 v[220:221], off
	v_lshl_add_u64 v[220:221], s[26:27], 0, v[178:179]
	s_mov_b32 m0, s38
	s_nop 0
	global_load_lds_dwordx4 v[220:221], off
	s_waitcnt vmcnt(8)
	s_waitcnt lgkmcnt(0)
	s_setprio 1
	s_waitcnt lgkmcnt(0)
	v_mfma_f32_16x16x32_bf16 v[124:127], v[128:131], v[160:163], v[124:127]
	v_mfma_f32_16x16x32_bf16 v[120:123], v[136:139], v[160:163], v[120:123]
	v_mfma_f32_16x16x32_bf16 v[112:115], v[128:131], v[168:171], v[112:115]
	v_mfma_f32_16x16x32_bf16 v[104:107], v[136:139], v[168:171], v[104:107]
	s_barrier
; #define PG8_STAGE(bufoff, gbase, voff) do { _Pragma("unroll") for (int _i = 0; _i < 2; ++_i) \
;         __builtin_amdgcn_global_load_lds((const unsigned*)((const char*)(gbase) + (voff)[_i]), (LAS unsigned*)(lds + (bufoff) + ldsw + _i * 8192), 16, 0, 0); } while (0)
; #define PG8_LDA(dst, b, h) do { _Pragma("unroll") for (int m = 0; m < 4; ++m) _Pragma("unroll") for (int k = 0; k < 2; ++k) dst[m][k] = *(const LAS bf16x8*)(lds + PG8_SA(b, h) + aoff + m * 2048 + k * 1024); } while (0)
; #define PG8_LDB(dst, b, h) do { _Pragma("unroll") for (int n = 0; n < 2; ++n) _Pragma("unroll") for (int k = 0; k < 2; ++k) dst[n][k] = *(const LAS bf16x8*)(lds + PG8_SB(b, h) + boff + n * 2048 + k * 1024); } while (0)
; #define PG8_MMA(ai, bj, At, Bt) do { __builtin_amdgcn_s_setprio(1); _Pragma("unroll") for (int m = 0; m < 4; ++m) _Pragma("unroll") for (int n = 0; n < 2; ++n) _Pragma("unroll") for (int k = 0; k < 2; ++k) \
;         acc[ai][bj][m][n] = __builtin_amdgcn_mfma_f32_16x16x32_bf16(Bt[n][k], At[m][k], acc[ai][bj][m][n], 0, 0, 0); __builtin_amdgcn_s_setprio(0); } while (0)
; #define PG8_WAIT_V(n) asm volatile("s_waitcnt vmcnt(" #n ")" ::: "memory")
; #define PG8_WAIT_L(n) asm volatile("s_waitcnt lgkmcnt(" #n ")" ::: "memory")
; #define PG8_BAR __builtin_amdgcn_s_barrier()
; #define PG8_SCHED __builtin_amdgcn_sched_barrier(0)
; template <class Epi, bool ALIGN_EPI, bool SP2>
; __device__ __forceinline__ void gemm_phase(LAS unsigned char* lds, const int K, const Sched& S, const Epi& E) {
;     ...
;             PG8_LDB(B0, 1, 0); PG8_LDB(B1, 1, 1); PG8_SCHED; PG8_LDA(At, 1, 0); PG8_STAGE(PG8_SA(0, 1), a2 + hstep, voffA);
;             PG8_WAIT_V(8); PG8_WAIT_L(0); PG8_BAR; PG8_MMA(0, 0, At, B0); PG8_MMA(0, 1, At, B1); PG8_BAR; PG8_SCHED;
;             PG8_LDA(At, 1, 1); PG8_STAGE(PG8_SB(1, 0), b3, voffB); PG8_STAGE(PG8_SB(1, 1), b3 + hstep, voffB); PG8_STAGE(PG8_SA(1, 0), a3, voffA);
;             PG8_WAIT_V(8); PG8_WAIT_L(0); PG8_BAR; PG8_MMA(1, 0, At, B0); PG8_MMA(1, 1, At, B1); PG8_BAR; PG8_SCHED;
	v_mfma_f32_16x16x32_bf16 v[96:99], v[128:131], v[188:191], v[96:99]
	v_mfma_f32_16x16x32_bf16 v[88:91], v[136:139], v[188:191], v[88:91]
	v_mfma_f32_16x16x32_bf16 v[80:83], v[128:131], v[196:199], v[80:83]
	v_mfma_f32_16x16x32_bf16 v[72:75], v[136:139], v[196:199], v[72:75]
	v_mfma_f32_16x16x32_bf16 v[124:127], v[132:135], v[164:167], v[124:127]
	v_mfma_f32_16x16x32_bf16 v[120:123], v[140:143], v[164:167], v[120:123]
	v_mfma_f32_16x16x32_bf16 v[112:115], v[132:135], v[172:175], v[112:115]
	v_mfma_f32_16x16x32_bf16 v[104:107], v[140:143], v[172:175], v[104:107]
	v_mfma_f32_16x16x32_bf16 v[96:99], v[132:135], v[192:195], v[96:99]
	v_mfma_f32_16x16x32_bf16 v[88:91], v[140:143], v[192:195], v[88:91]
	v_mfma_f32_16x16x32_bf16 v[80:83], v[132:135], v[208:211], v[80:83]
	v_mfma_f32_16x16x32_bf16 v[72:75], v[140:143], v[208:211], v[72:75]
	s_setprio 0
	s_setprio 1
	v_mfma_f32_16x16x32_bf16 v[116:119], v[144:147], v[160:163], v[116:119]
	v_mfma_f32_16x16x32_bf16 v[108:111], v[152:155], v[160:163], v[108:111]
	v_mfma_f32_16x16x32_bf16 v[100:103], v[144:147], v[168:171], v[100:103]
	v_mfma_f32_16x16x32_bf16 v[92:95], v[152:155], v[168:171], v[92:95]
	v_mfma_f32_16x16x32_bf16 v[84:87], v[144:147], v[188:191], v[84:87]
	v_mfma_f32_16x16x32_bf16 v[76:79], v[152:155], v[188:191], v[76:79]
	v_mfma_f32_16x16x32_bf16 v[68:71], v[144:147], v[196:199], v[68:71]
	v_mfma_f32_16x16x32_bf16 v[64:67], v[152:155], v[196:199], v[64:67]
	v_mfma_f32_16x16x32_bf16 v[116:119], v[148:151], v[164:167], v[116:119]
	v_mfma_f32_16x16x32_bf16 v[108:111], v[156:159], v[164:167], v[108:111]
	v_mfma_f32_16x16x32_bf16 v[100:103], v[148:151], v[172:175], v[100:103]
	v_mfma_f32_16x16x32_bf16 v[92:95], v[156:159], v[172:175], v[92:95]
	v_mfma_f32_16x16x32_bf16 v[84:87], v[148:151], v[192:195], v[84:87]
	v_mfma_f32_16x16x32_bf16 v[76:79], v[156:159], v[192:195], v[76:79]
	v_mfma_f32_16x16x32_bf16 v[68:71], v[148:151], v[208:211], v[68:71]
	v_mfma_f32_16x16x32_bf16 v[64:67], v[156:159], v[208:211], v[64:67]
	s_setprio 0
	s_barrier
	s_add_i32 s26, s51, s34
	v_lshl_add_u64 v[212:213], v[212:213], 0, s[8:9]
	s_mov_b32 m0, s26
	ds_read_b128 v[160:163], v205 offset:49152
	ds_read_b128 v[164:167], v205 offset:50176
	ds_read_b128 v[168:171], v205 offset:51200
	ds_read_b128 v[172:175], v205 offset:52224
	ds_read_b128 v[188:191], v205 offset:53248
	ds_read_b128 v[192:195], v205 offset:54272
	ds_read_b128 v[196:199], v205 offset:55296
	ds_read_b128 v[208:211], v205 offset:56320
	global_load_lds_dwordx4 v[212:213], off
	s_add_i32 m0, s26, 0x2000
	s_add_u32 s24, s24, 0x100080
	v_lshl_add_u64 v[212:213], v[214:215], 0, s[8:9]
	s_addc_u32 s25, s25, 0
	s_add_i32 s26, s53, s34
	global_load_lds_dwordx4 v[212:213], off
	v_lshl_add_u64 v[212:213], s[24:25], 0, v[180:181]
	s_mov_b32 m0, s26
	s_nop 0
	global_load_lds_dwordx4 v[212:213], off
	v_lshl_add_u64 v[212:213], s[24:25], 0, v[176:177]
	s_add_i32 m0, s26, 0x2000
	s_nop 0
	global_load_lds_dwordx4 v[212:213], off
	v_lshl_add_u64 v[212:213], v[216:217], 0, s[100:101]
	s_mov_b32 m0, s41
	s_nop 0
	global_load_lds_dwordx4 v[212:213], off
	v_lshl_add_u64 v[212:213], v[218:219], 0, s[100:101]
	s_mov_b32 m0, s42
	s_nop 0
	global_load_lds_dwordx4 v[212:213], off
	s_waitcnt vmcnt(8)
	s_waitcnt lgkmcnt(0)
	s_setprio 1
	s_waitcnt lgkmcnt(0)
	v_mfma_f32_16x16x32_bf16 v[60:63], v[128:131], v[160:163], v[60:63]
	v_mfma_f32_16x16x32_bf16 v[56:59], v[136:139], v[160:163], v[56:59]
	v_mfma_f32_16x16x32_bf16 v[48:51], v[128:131], v[168:171], v[48:51]
	v_mfma_f32_16x16x32_bf16 v[40:43], v[136:139], v[168:171], v[40:43]
	s_barrier
	v_mfma_f32_16x16x32_bf16 v[32:35], v[128:131], v[188:191], v[32:35]
	v_mfma_f32_16x16x32_bf16 v[24:27], v[136:139], v[188:191], v[24:27]
	v_mfma_f32_16x16x32_bf16 v[16:19], v[128:131], v[196:199], v[16:19]
	v_mfma_f32_16x16x32_bf16 v[8:11], v[136:139], v[196:199], v[8:11]
	v_mfma_f32_16x16x32_bf16 v[60:63], v[132:135], v[164:167], v[60:63]
	v_mfma_f32_16x16x32_bf16 v[56:59], v[140:143], v[164:167], v[56:59]
	v_mfma_f32_16x16x32_bf16 v[48:51], v[132:135], v[172:175], v[48:51]
	v_mfma_f32_16x16x32_bf16 v[40:43], v[140:143], v[172:175], v[40:43]
	v_mfma_f32_16x16x32_bf16 v[32:35], v[132:135], v[192:195], v[32:35]
	v_mfma_f32_16x16x32_bf16 v[24:27], v[140:143], v[192:195], v[24:27]
	v_mfma_f32_16x16x32_bf16 v[16:19], v[132:135], v[208:211], v[16:19]
	v_mfma_f32_16x16x32_bf16 v[8:11], v[140:143], v[208:211], v[8:11]
	s_setprio 0
	s_setprio 1
	v_mfma_f32_16x16x32_bf16 v[52:55], v[144:147], v[160:163], v[52:55]
	v_mfma_f32_16x16x32_bf16 v[44:47], v[152:155], v[160:163], v[44:47]
	v_mfma_f32_16x16x32_bf16 v[36:39], v[144:147], v[168:171], v[36:39]
	v_mfma_f32_16x16x32_bf16 v[28:31], v[152:155], v[168:171], v[28:31]
	v_mfma_f32_16x16x32_bf16 v[20:23], v[144:147], v[188:191], v[20:23]
	v_mfma_f32_16x16x32_bf16 v[12:15], v[152:155], v[188:191], v[12:15]
	v_mfma_f32_16x16x32_bf16 v[4:7], v[144:147], v[196:199], v[4:7]
	v_mfma_f32_16x16x32_bf16 v[0:3], v[152:155], v[196:199], v[0:3]
	v_mfma_f32_16x16x32_bf16 v[52:55], v[148:151], v[164:167], v[52:55]
	v_mfma_f32_16x16x32_bf16 v[44:47], v[156:159], v[164:167], v[44:47]
	v_mfma_f32_16x16x32_bf16 v[36:39], v[148:151], v[172:175], v[36:39]
	v_mfma_f32_16x16x32_bf16 v[28:31], v[156:159], v[172:175], v[28:31]
	v_mfma_f32_16x16x32_bf16 v[20:23], v[148:151], v[192:195], v[20:23]
	v_mfma_f32_16x16x32_bf16 v[12:15], v[156:159], v[192:195], v[12:15]
	v_mfma_f32_16x16x32_bf16 v[4:7], v[148:151], v[208:211], v[4:7]
	v_mfma_f32_16x16x32_bf16 v[0:3], v[156:159], v[208:211], v[0:3]
	s_setprio 0
	s_barrier
	s_add_i32 s50, s50, 2
	s_add_u32 s22, s22, 0x10000
	s_addc_u32 s23, s23, 0
	s_add_u32 s48, s48, 0x100
	s_addc_u32 s49, s49, 0
	s_cmp_gt_u32 s50, 61
	s_cbranch_scc0 .LBB0_1179
	s_and_b64 vcc, exec, s[10:11]
	s_cbranch_vccz .LBB0_1182
	s_barrier
